# attention main loop: next key step's K fragments fetched one step ahead (LDS reads off the QK critical path)
# speedup vs baseline: 1.0021x; 1.0021x over previous
; __device__ __forceinline__ void qk_prep_store(u32x4 a, u32x4 b, const float* gain, int sub, int pos, float scale, bf16_t* dst, int lane) {
;     ...
;     u32x4 o0, o1;
;     o0.x = pk2(x[0] * scale, x[1] * scale); o0.y = pk2(x[2] * scale, x[3] * scale); o0.z = pk2(x[4] * scale, x[5] * scale); o0.w = pk2(x[6] * scale, x[7] * scale);
;     o1.x = pk2(x[8] * scale, x[9] * scale); o1.y = pk2(x[10] * scale, x[11] * scale); o1.z = pk2(x[12] * scale, x[13] * scale); o1.w = pk2(x[14] * scale, x[15] * scale);
;     *(u32x4*)dst = o0; *(u32x4*)(dst + 8) = o1;
; __device__ __forceinline__ void ph_attn(KP p, int l, unsigned char* sm, int wv) {
;     ...
;             __syncthreads();
;             bf16x8 qf[2];
; #pragma unroll
;             for (int ks = 0; ks < 2; ++ks) qf[ks] = *(const bf16x8*)(Qs + (16 * wid + fr) * 72 + 32 * ks + 8 * fq);
;             f32x4 o[4];
; #pragma unroll
;             for (int dt = 0; dt < 4; ++dt) o[dt] = (f32x4){0.f, 0.f, 0.f, 0.f};
;             float mrun = p->sink[l * 8 + h] * 1.4426950408889634f;
;             float lsum = fq == 0 ? 1.0f : 0.0f;
;             const int qi = 16 * wid + fr;
;             for (int s = 0; s < 9; ++s) {
;                 const int kk0 = 16 * wid + 32 * s;
;                 f32x4 st[2];
; #pragma unroll
;                 for (int kt = 0; kt < 2; ++kt) {
;                     st[kt] = (f32x4){0.f, 0.f, 0.f, 0.f};
; #pragma unroll
;                     for (int ks = 0; ks < 2; ++ks) {
;                         const bf16x8 kf = *(const bf16x8*)(Ks + (kk0 + 16 * kt + fr) * 72 + 32 * ks + 8 * fq);
;                         st[kt] = __builtin_amdgcn_mfma_f32_16x16x32_bf16(kf, qf[ks], st[kt], 0, 0, 0);
;                     }
;                 }
;                 float sv[2][4]; float mx = -1e30f;
;                 if (interior && s >= 1 && s <= 7) {
; #pragma unroll
;                     for (int kt = 0; kt < 2; ++kt)
; #pragma unroll
;                         for (int r = 0; r < 4; ++r) { sv[kt][r] = st[kt][r]; mx = fmaxf(mx, sv[kt][r]); }
;                 } else {
; #pragma unroll
;                     for (int kt = 0; kt < 2; ++kt)
; #pragma unroll
;                         for (int r = 0; r < 4; ++r) {
;                             const int kk = kk0 + 16 * kt + 4 * fq + r, d = kk - 128 - qi, prel = Q0rel + kk - 128;
.LBB0_846:
	s_or_b64 exec, exec, s[2:3]
	v_mul_f32_e32 v41, 0x3e38aa3b, v50
	v_mul_f32_e32 v43, 0x3e38aa3b, v51
	v_cvt_pk_bf16_f32 v50, v41, v43
	v_mul_f32_e32 v41, 0x3e38aa3b, v48
	v_mul_f32_e32 v43, 0x3e38aa3b, v49
	v_cvt_pk_bf16_f32 v51, v41, v43
	v_mul_f32_e32 v41, 0x3e38aa3b, v46
	v_mul_f32_e32 v34, 0x3e38aa3b, v34
	v_mul_f32_e32 v35, 0x3e38aa3b, v35
	v_readlane_b32 s2, v254, 22
	v_mul_f32_e32 v43, 0x3e38aa3b, v47
	v_cvt_pk_bf16_f32 v52, v41, v43
	v_mul_f32_e32 v41, 0x3e38aa3b, v42
	v_mul_f32_e32 v42, 0x3e38aa3b, v45
	v_cvt_pk_bf16_f32 v53, v41, v42
	v_mul_f32_e32 v38, 0x3e38aa3b, v38
	v_mul_f32_e32 v39, 0x3e38aa3b, v39
	v_cvt_pk_bf16_f32 v46, v38, v39
	v_mul_f32_e32 v36, 0x3e38aa3b, v36
	v_mul_f32_e32 v37, 0x3e38aa3b, v37
	v_cvt_pk_bf16_f32 v47, v36, v37
	v_cvt_pk_bf16_f32 v48, v34, v35
	v_mul_f32_e32 v34, 0x3e38aa3b, v40
	v_mul_f32_e32 v35, 0x3e38aa3b, v44
	v_readlane_b32 s3, v254, 23
	v_cvt_pk_bf16_f32 v49, v34, v35
	ds_write_b128 v98, v[50:53]
	ds_write_b128 v98, v[46:49] offset:16
	s_waitcnt lgkmcnt(0)
	s_barrier
	ds_read_b128 v[38:41], v156
	ds_read_b128 v[34:37], v156 offset:64
	s_load_dwordx2 s[2:3], s[2:3], 0x40
	s_add_i32 s40, s39, s38
	s_add_i32 s18, s40, s31
	s_ashr_i32 s19, s18, 31
	s_lshl_b64 s[18:19], s[18:19], 2
	s_waitcnt lgkmcnt(0)
	s_add_u32 s2, s2, s18
	s_addc_u32 s3, s3, s19
	global_load_dword v54, v1, s[2:3]
	v_add_u32_e32 v50, v102, v100
	ds_read_b128 v[42:45], v50
	ds_read_b128 v[46:49], v50 offset:64
	ds_read_b128 v[224:227], v50 offset:2304
	ds_read_b128 v[182:185], v50 offset:2368
	s_waitcnt lgkmcnt(3)
	v_mfma_f32_16x16x32_bf16 v[42:45], v[42:45], v[38:41], 0
	s_mov_b32 s2, 0x3fb8aa3b
	v_add_u32_e32 v159, 0xe000, v140
	s_mov_b32 s42, 0
	s_waitcnt lgkmcnt(2)
	v_mfma_f32_16x16x32_bf16 v[42:45], v[46:49], v[34:37], v[42:45]
	ds_read2_b64 v[186:189], v159 offset0:32 offset1:36
	ds_read2_b64 v[198:201], v150 offset1:4
	ds_read2_b64 v[190:193], v148 offset1:4
	ds_read2_b64 v[194:197], v149 offset1:4
	s_waitcnt vmcnt(0)
	v_mul_f32_e32 v55, 0x3fb8aa3b, v54
	s_waitcnt lgkmcnt(5)
	v_mfma_f32_16x16x32_bf16 v[46:49], v[224:227], v[38:41], 0
	s_nop 1
	v_cndmask_b32_e64 v42, v243, v42, s[88:89]
	v_cndmask_b32_e64 v43, v243, v43, s[90:91]
	v_cndmask_b32_e64 v44, v243, v44, s[92:93]
	s_waitcnt lgkmcnt(4)
	v_mfma_f32_16x16x32_bf16 v[46:49], v[182:185], v[34:37], v[46:49]
	v_max3_f32 v50, v42, s35, v43
	v_cndmask_b32_e64 v45, v243, v45, s[94:95]
	v_max3_f32 v50, v50, v44, v45
	s_nop 4
	v_cndmask_b32_e64 v46, v243, v46, s[96:97]
	v_cndmask_b32_e64 v47, v243, v47, s[16:17]
	v_max3_f32 v50, v50, v46, v47
	v_cndmask_b32_e64 v48, v243, v48, s[14:15]
	v_cndmask_b32_e64 v49, v243, v49, s[0:1]
	v_max3_f32 v50, v50, v48, v49
	v_mov_b32_e32 v51, v50
	s_nop 1
	v_permlane16_swap_b32_e32 v50, v51
	s_nop 0
	s_waitcnt lgkmcnt(0)
	v_max_f32_e32 v51, v51, v51
	v_max_f32_e32 v50, v50, v51
	v_mov_b32_e32 v51, v50
	s_nop 1
	v_permlane32_swap_b32_e32 v50, v51
	s_nop 0
	s_waitcnt lgkmcnt(0)
	v_max3_f32 v163, v55, v50, v51
	v_sub_f32_e32 v42, v42, v163
	v_exp_f32_e32 v59, v42
	v_sub_f32_e32 v42, v43, v163
	v_exp_f32_e32 v64, v42
	v_sub_f32_e32 v42, v44, v163
	v_exp_f32_e32 v65, v42
	v_sub_f32_e32 v42, v45, v163
	v_exp_f32_e32 v160, v42
	v_sub_f32_e32 v42, v46, v163
	v_exp_f32_e32 v161, v42
	v_sub_f32_e32 v42, v47, v163
	v_exp_f32_e32 v162, v42
	v_sub_f32_e32 v42, v48, v163
	v_fma_f32 v50, v54, s2, -v163
	v_exp_f32_e32 v168, v42
	v_sub_f32_e32 v42, v49, v163
	v_exp_f32_e32 v169, v42
	v_exp_f32_e32 v58, v50
	v_cvt_pk_bf16_f32 v54, v59, v64
	v_cvt_pk_bf16_f32 v55, v65, v160
	v_cvt_pk_bf16_f32 v56, v161, v162
	v_cvt_pk_bf16_f32 v57, v168, v169
	s_nop 0
	v_cmp_neq_f32_e32 vcc, 1.0, v58
	s_cmp_eq_u64 vcc, 0
	s_cselect_b64 s[2:3], -1, 0
	v_mul_f32_e32 v46, 0, v58
	v_cndmask_b32_e64 v60, v46, 0, s[2:3]
	v_mov_b32_e32 v61, v60
	v_mov_b32_e32 v62, v60
	v_mov_b32_e32 v63, v60
	s_nop 0
	s_waitcnt lgkmcnt(0)
	v_mfma_f32_16x16x32_bf16 v[46:49], v[186:189], v[54:57], v[60:63]
	s_nop 0
	s_waitcnt lgkmcnt(0)
	v_mfma_f32_16x16x32_bf16 v[50:53], v[190:193], v[54:57], v[60:63]
	s_nop 0
	s_waitcnt lgkmcnt(0)
	v_mfma_f32_16x16x32_bf16 v[42:45], v[194:197], v[54:57], v[60:63]
	s_nop 2
	v_mul_f32_e64 v60, v58, 0
	v_mul_f32_e64 v61, v58, 0
	v_add_f32_e32 v59, 0, v59
	v_add_f32_e32 v59, v64, v59
	v_add_f32_e32 v59, v65, v59
	v_cndmask_b32_e64 v61, v61, 0, s[2:3]
	v_cndmask_b32_e64 v60, v60, 0, s[2:3]
	v_add_f32_e32 v59, v160, v59
	v_mov_b32_e32 v62, v60
	v_mov_b32_e32 v63, v61
	v_add_f32_e32 v59, v161, v59
	v_add_f32_e32 v59, v162, v59
	v_mfma_f32_16x16x32_bf16 v[54:57], v[198:201], v[54:57], v[60:63]
	v_add_f32_e32 v59, v168, v59
	v_add_f32_e32 v162, v169, v59
	v_fmac_f32_e32 v162, v101, v58
	v_mov_b32_e32 v160, v152
	v_mov_b32_e32 v161, v151
	ds_read_b128 v[186:189], v160
	ds_read_b128 v[190:193], v160 offset:64
	ds_read_b128 v[194:197], v160 offset:2304
	ds_read_b128 v[198:201], v160 offset:2368
; __device__ __forceinline__ void ph_attn(KP p, int l, unsigned char* sm, int wv) {
;     ...
;             for (int s = 0; s < 9; ++s) {
;                 const int kk0 = 16 * wid + 32 * s;
;                 f32x4 st[2];
; #pragma unroll
;                 for (int kt = 0; kt < 2; ++kt) {
;                     st[kt] = (f32x4){0.f, 0.f, 0.f, 0.f};
; #pragma unroll
;                     for (int ks = 0; ks < 2; ++ks) {
;                         const bf16x8 kf = *(const bf16x8*)(Ks + (kk0 + 16 * kt + fr) * 72 + 32 * ks + 8 * fq);
;                         st[kt] = __builtin_amdgcn_mfma_f32_16x16x32_bf16(kf, qf[ks], st[kt], 0, 0, 0);
;                     }
;                 }
;                 float sv[2][4]; float mx = -1e30f;
;                 if (interior && s >= 1 && s <= 7) {
; #pragma unroll
;                     for (int kt = 0; kt < 2; ++kt)
; #pragma unroll
;                         for (int r = 0; r < 4; ++r) { sv[kt][r] = st[kt][r]; mx = fmaxf(mx, sv[kt][r]); }
;                 } else {
; #pragma unroll
;                     for (int kt = 0; kt < 2; ++kt)
; #pragma unroll
;                         for (int r = 0; r < 4; ++r) {
;                             const int kk = kk0 + 16 * kt + 4 * fq + r, d = kk - 128 - qi, prel = Q0rel + kk - 128;
;                             const bool valid = d >= -128 && d <= 128 && prel >= 0 && prel < L && kk < 384;
;                             sv[kt][r] = valid ? st[kt][r] : -1e30f;
;                             mx = fmaxf(mx, sv[kt][r]);
;                         }
;                 }
.LBB0_847:
	s_mov_b64 s[2:3], -1
	s_and_b64 vcc, exec, s[36:37]
	s_waitcnt lgkmcnt(0)
	v_mfma_f32_16x16x32_bf16 v[58:61], v[186:189], v[38:41], 0
	v_mfma_f32_16x16x32_bf16 v[58:61], v[190:193], v[34:37], v[58:61]
	v_mfma_f32_16x16x32_bf16 v[62:65], v[194:197], v[38:41], 0
	v_mfma_f32_16x16x32_bf16 v[62:65], v[198:201], v[34:37], v[62:65]
	s_cbranch_vccz .LBB0_849
	v_add_u32_e32 v164, s42, v144
	v_add_u32_e32 v172, s42, v158
	v_add_u32_e32 v165, 32, v164
	v_add_u32_e32 v166, 32, v172
	v_cmp_gt_i32_e64 s[2:3], s41, v166
	v_cmp_gt_i32_e32 vcc, s21, v165
	v_cmp_lt_i32_e64 s[18:19], s33, v166
	s_and_b64 s[2:3], vcc, s[2:3]
	v_add_u32_e32 v166, 33, v164
	v_add_u32_e32 v167, 33, v172
	s_and_b64 vcc, s[18:19], s[2:3]
	v_cmp_gt_i32_e64 s[2:3], s41, v167
	v_cmp_gt_i32_e64 s[18:19], s21, v166
	v_cndmask_b32_e32 v171, v243, v58, vcc
	v_cmp_lt_i32_e32 vcc, s33, v167
	s_and_b64 s[2:3], s[18:19], s[2:3]
	v_add_u32_e32 v167, 34, v164
	v_add_u32_e32 v168, 34, v172
	s_and_b64 vcc, vcc, s[2:3]
	v_cmp_gt_i32_e64 s[2:3], s41, v168
	v_cmp_gt_i32_e64 s[18:19], s21, v167
	v_cndmask_b32_e32 v170, v243, v59, vcc
	v_cmp_lt_i32_e32 vcc, s33, v168
	s_and_b64 s[2:3], s[18:19], s[2:3]
	v_add_u32_e32 v164, 35, v164
	v_add_u32_e32 v167, 35, v172
	s_and_b64 vcc, vcc, s[2:3]
	v_cmp_gt_i32_e64 s[2:3], s41, v167
	v_cmp_gt_i32_e64 s[18:19], s21, v164
	v_cndmask_b32_e32 v169, v243, v60, vcc
	v_cmp_lt_i32_e32 vcc, s33, v167
	s_and_b64 s[2:3], s[18:19], s[2:3]
	s_and_b64 vcc, vcc, s[2:3]
	v_max3_f32 v166, v171, s35, v170
	v_cndmask_b32_e32 v168, v243, v61, vcc
	v_max3_f32 v164, v166, v169, v168
	v_add_u32_e32 v166, 48, v172
	v_cmp_gt_i32_e64 s[2:3], s41, v166
	v_cmp_gt_i32_e64 s[18:19], s46, v165
	v_cmp_lt_i32_e32 vcc, s33, v166
	s_and_b64 s[2:3], s[18:19], s[2:3]
	v_add_u32_e32 v167, 49, v172
	s_and_b64 vcc, vcc, s[2:3]
	v_cmp_gt_i32_e64 s[2:3], s41, v167
	v_cmp_gt_i32_e64 s[18:19], s47, v165
	v_cndmask_b32_e32 v166, v243, v62, vcc
	v_cmp_lt_i32_e32 vcc, s33, v167
	s_and_b64 s[2:3], s[18:19], s[2:3]
	s_and_b64 vcc, vcc, s[2:3]
	v_cndmask_b32_e32 v167, v243, v63, vcc
	v_max3_f32 v173, v164, v166, v167
	v_add_u32_e32 v164, 50, v172
	v_cmp_gt_i32_e64 s[2:3], s41, v164
	v_cmp_gt_i32_e64 s[18:19], s48, v165
	v_cmp_lt_i32_e32 vcc, s33, v164
	s_and_b64 s[2:3], s[18:19], s[2:3]
	v_add_u32_e32 v172, 51, v172
	s_and_b64 vcc, vcc, s[2:3]
	v_cmp_gt_i32_e64 s[2:3], s41, v172
	v_cmp_gt_i32_e64 s[18:19], s49, v165
	v_cndmask_b32_e32 v164, v243, v64, vcc
	v_cmp_lt_i32_e32 vcc, s33, v172
	s_and_b64 s[2:3], s[18:19], s[2:3]
	s_and_b64 vcc, vcc, s[2:3]
	v_cndmask_b32_e32 v165, v243, v65, vcc
	v_max3_f32 v172, v173, v164, v165
	s_mov_b64 s[2:3], 0

; __device__ __forceinline__ unsigned pk2(float lo, float hi) { unsigned r; asm volatile("v_cvt_pk_bf16_f32 %0, %1, %2" : "=v"(r) : "v"(lo), "v"(hi)); return r; }
; __device__ __forceinline__ float shx(float v, int mask, int lane) { return __int_as_float(__builtin_amdgcn_ds_bpermute((lane ^ mask) << 2, __float_as_int(v))); }
; __device__ __forceinline__ void ph_attn(KP p, int l, unsigned char* sm, int wv) {
;     ...
;                 mx = fmaxf(mx, shx(mx, 16, lane)); mx = fmaxf(mx, shx(mx, 32, lane));
;                 const float mn = fmaxf(mrun, mx), alpha = __builtin_amdgcn_exp2f(mrun - mn);
;                 mrun = mn;
;                 float pr[2][4], psum = 0.f;
; #pragma unroll
;                 for (int kt = 0; kt < 2; ++kt)
; #pragma unroll
;                     for (int r = 0; r < 4; ++r) { pr[kt][r] = __builtin_amdgcn_exp2f(sv[kt][r] - mn); psum += pr[kt][r]; }
;                 lsum = lsum * alpha + psum;
;                 const bool rescale = __builtin_amdgcn_ballot_w64(alpha != 1.0f) != 0ull;
;                 union { bf16x8 v; unsigned u[4]; } pf;
;                 pf.u[0] = pk2(pr[0][0], pr[0][1]); pf.u[1] = pk2(pr[0][2], pr[0][3]); pf.u[2] = pk2(pr[1][0], pr[1][1]); pf.u[3] = pk2(pr[1][2], pr[1][3]);
; #pragma unroll
;                 for (int dt = 0; dt < 4; ++dt) {
;                     if (rescale) o[dt] = o[dt] * alpha;
;                     union { bf16x8 v; u32x2 h[2]; } vf;
;                     vf.h[0] = *(const u32x2*)(Vt + (16 * dt + fr) * 404 + kk0 + 4 * fq);
;                     vf.h[1] = *(const u32x2*)(Vt + (16 * dt + fr) * 404 + kk0 + 16 + 4 * fq);
;                     o[dt] = __builtin_amdgcn_mfma_f32_16x16x32_bf16(vf.v, pf.v, o[dt], 0, 0, 0);
;                 }
.LBB0_851:
	v_max_f32_e32 v59, v172, v172
	v_mov_b32_e32 v58, v59
	v_add_u32_e32 v172, 0, v161
	v_add_u32_e32 v222, 0xe000, v172
	ds_read2_b64 v[206:209], v222 offset0:40 offset1:44
	ds_read_b64 v[210:211], v222 offset:13248
	ds_read_b64 v[212:213], v222 offset:13280
	ds_read_b64 v[214:215], v222 offset:26176
	ds_read_b64 v[216:217], v222 offset:26208
	ds_read_b64 v[218:219], v222 offset:39104
	ds_read_b64 v[220:221], v222 offset:39136
	v_permlane16_swap_b32_e32 v59, v58
	v_add_u32_e32 v161, 64, v161
	v_add_u32_e32 v160, 0x1200, v160
	ds_read_b128 v[186:189], v160
	ds_read_b128 v[190:193], v160 offset:64
	ds_read_b128 v[194:197], v160 offset:2304
	ds_read_b128 v[198:201], v160 offset:2368
	v_max_f32_e32 v58, v59, v58
	v_mov_b32_e32 v59, v58
	s_nop 1
	v_permlane32_swap_b32_e32 v58, v59
	s_nop 0
	v_max3_f32 v63, v163, v58, v59
	v_sub_f32_e32 v59, v171, v63
	v_exp_f32_e32 v59, v59
	v_sub_f32_e32 v61, v170, v63
	v_exp_f32_e32 v61, v61
	v_sub_f32_e32 v62, v169, v63
	v_sub_f32_e32 v58, v163, v63
	v_exp_f32_e32 v64, v62
	v_sub_f32_e32 v62, v168, v63
	v_exp_f32_e32 v65, v62
	v_exp_f32_e32 v62, v58
	v_add_f32_e32 v60, 0, v59
	v_add_f32_e32 v60, v61, v60
	v_add_f32_e32 v60, v64, v60
	v_add_f32_e32 v163, v65, v60
	v_sub_f32_e32 v60, v166, v63
	v_cmp_neq_f32_e32 vcc, 1.0, v62
	v_exp_f32_e32 v168, v60
	v_sub_f32_e32 v60, v167, v63
	s_cmp_eq_u64 vcc, 0
	v_exp_f32_e32 v169, v60
	v_sub_f32_e32 v60, v164, v63
	s_cselect_b64 vcc, -1, 0
	v_cvt_pk_bf16_f32 v58, v59, v61
	v_cvt_pk_bf16_f32 v59, v64, v65
	v_pk_mul_f32 v[64:65], v[46:47], v[62:63] op_sel_hi:[1,0]
	v_exp_f32_e32 v170, v60
	v_sub_f32_e32 v60, v165, v63
	v_pk_mul_f32 v[164:165], v[48:49], v[62:63] op_sel_hi:[1,0]
	v_cndmask_b32_e32 v46, v64, v46, vcc
	v_exp_f32_e32 v171, v60
	v_cvt_pk_bf16_f32 v60, v168, v169
	v_cvt_pk_bf16_f32 v61, v170, v171
	v_cndmask_b32_e32 v49, v165, v49, vcc
	v_cndmask_b32_e32 v48, v164, v48, vcc
	v_cndmask_b32_e32 v47, v65, v47, vcc
	v_pk_mul_f32 v[64:65], v[62:63], v[52:53] op_sel_hi:[0,1]
	v_cndmask_b32_e32 v52, v64, v52, vcc
	s_waitcnt lgkmcnt(0)
	v_mfma_f32_16x16x32_bf16 v[46:49], v[206:209], v[58:61], v[46:49]
	v_mul_f32_e64 v164, v62, v50
	v_mul_f32_e64 v165, v62, v51
	v_cndmask_b32_e32 v51, v165, v51, vcc
	v_cndmask_b32_e32 v50, v164, v50, vcc
	v_cndmask_b32_e32 v53, v65, v53, vcc
	v_pk_mul_f32 v[64:65], v[62:63], v[44:45] op_sel_hi:[0,1]
	v_cndmask_b32_e32 v44, v64, v44, vcc
	s_nop 0
	v_mfma_f32_16x16x32_bf16 v[50:53], v[210:213], v[58:61], v[50:53]
	v_mul_f32_e64 v164, v62, v42
	v_mul_f32_e64 v165, v62, v43
	v_cndmask_b32_e32 v43, v165, v43, vcc
	v_cndmask_b32_e32 v42, v164, v42, vcc
	v_cndmask_b32_e32 v45, v65, v45, vcc
	v_pk_mul_f32 v[64:65], v[62:63], v[56:57] op_sel_hi:[0,1]
	v_cndmask_b32_e32 v56, v64, v56, vcc
	s_nop 0
	v_mfma_f32_16x16x32_bf16 v[42:45], v[214:217], v[58:61], v[42:45]
	v_mul_f32_e64 v164, v62, v54
	v_mul_f32_e64 v165, v62, v55
	v_cndmask_b32_e32 v55, v165, v55, vcc
	v_cndmask_b32_e32 v54, v164, v54, vcc
	v_cndmask_b32_e32 v57, v65, v57, vcc
	s_add_i32 s42, s42, 32
	s_cmpk_eq_i32 s42, 0xe0
	s_nop 0
	v_mfma_f32_16x16x32_bf16 v[54:57], v[218:221], v[58:61], v[54:57]
	v_add_f32_e32 v58, v168, v163
	v_add_f32_e32 v58, v169, v58
	v_add_f32_e32 v58, v170, v58
	v_add_f32_e32 v58, v171, v58
	v_fmac_f32_e32 v58, v162, v62
	s_cbranch_scc1 .LBB0_837
	v_mov_b32_e32 v163, v63
	v_mov_b32_e32 v162, v58
	s_branch .LBB0_847
